# P0 (weight / input conversion) f32 source loads marked nt: the once-read f32 weights and x no longer displace the bf16 working set from the caches
# speedup vs baseline: 1.0543x; 1.0543x over previous
; DI void tr_tile(const float* src, int ldsrc, u16* dst, int ldd, int k0, int n0, const float* g, int mode, char* lds) {
;   float* t = (float*)lds;
;   const int tid = threadIdx.x;
;   float v[16];
; #pragma unroll
;   for (int i = 0; i < 16; ++i) {
;     const int e = tid + 256 * i, kk = e >> 6, nn = e & 63;
;     const int sc = mapcol(n0 + nn, mode);
;     v[i] = sc >= 0 ? src[(size_t)(k0 + kk) * ldsrc + sc] : 0.f;
;   }
;   if (g) {
; #pragma unroll
;     for (int i = 0; i < 16; ++i) v[i] *= g[k0 + ((tid + 256 * i) >> 6)];
;   }
; #pragma unroll
;   for (int i = 0; i < 16; ++i) { const int e = tid + 256 * i, kk = e >> 6, nn = e & 63; t[kk * 65 + nn] = v[i]; }
;   __syncthreads();
; #pragma unroll
;   for (int i = 0; i < 2; ++i) {
;     const int e = tid + 256 * i, nn = e >> 3, k8 = (e & 7) * 8;
;     u32x4 o;
;     o[0] = pk2(t[(k8 + 0) * 65 + nn], t[(k8 + 1) * 65 + nn]); o[1] = pk2(t[(k8 + 2) * 65 + nn], t[(k8 + 3) * 65 + nn]);
;     o[2] = pk2(t[(k8 + 4) * 65 + nn], t[(k8 + 5) * 65 + nn]); o[3] = pk2(t[(k8 + 6) * 65 + nn], t[(k8 + 7) * 65 + nn]);
;     *(u32x4*)(dst + (size_t)(n0 + nn) * ldd + k0 + k8) = o;
;   }
;   __syncthreads();
; }
; __global__ void __launch_bounds__(256, 2) hybrid_megakernel(Params p) {
;     ...
;     else if (it < 5424) { const int mtx = it - 5408;
;       tr_tile(p.w_pool + (size_t)mtx * 4096, 64, (u16*)(ws_ + OFF_WPT) + (size_t)mtx * 4096, 64, 0, 0, nullptr, 0, lds); }
;     else { const int i2 = it - 5424, mtx = i2 >> 2, qd = i2 & 3;
;       const float* src = p.w_sp + (size_t)mtx * 16384 + qd * 4096; u16* dst = (u16*)(ws_ + OFF_WSP) + (size_t)mtx * 16384 + qd * 4096;
;       f32x4 v[4];
; #pragma unroll
;       for (int k = 0; k < 4; ++k) v[k] = *(const f32x4*)(src + (threadIdx.x + 256 * k) * 4);
; #pragma unroll
;       for (int k = 0; k < 4; ++k) {
;         const int e = qd * 4096 + (threadIdx.x + 256 * k) * 4, i = e >> 7, j = e & 127;
;         u32x2 o; o[0] = pk2(j <= i ? v[k][0] : 0.f, j + 1 <= i ? v[k][1] : 0.f); o[1] = pk2(j + 2 <= i ? v[k][2] : 0.f, j + 3 <= i ? v[k][3] : 0.f);
;         *(u32x2*)(dst + (threadIdx.x + 256 * k) * 4) = o;
;       } }
.LBB0_29:
	s_cmpk_gt_i32 s40, 0xcff
	s_mov_b64 s[4:5], -1
	s_cbranch_scc0 .LBB0_47
	s_cmpk_gt_u32 s40, 0x10ff
	s_cbranch_scc0 .LBB0_44
	s_cmpk_gt_u32 s40, 0x14ff
	s_cbranch_scc0 .LBB0_41
	s_cmpk_gt_u32 s40, 0x151f
	s_cbranch_scc0 .LBB0_38
	s_cmpk_gt_u32 s40, 0x152f
	s_cbranch_scc0 .LBB0_35
	s_add_i32 s2, s40, 0xffffead0
	s_lshr_b32 s2, s2, 2
	s_lshl_b64 s[4:5], s[2:3], 16
	s_add_u32 s4, s80, s4
	s_addc_u32 s5, s81, s5
	s_and_b32 s6, s20, 0x3000
	s_lshl_b32 s7, s6, 2
	s_add_u32 s4, s4, s7
	s_addc_u32 s5, s5, 0
	v_lshl_add_u64 v[30:31], v[0:1], 2, s[4:5]
	global_load_dwordx4 v[22:25], v[30:31], off nt
	v_add_co_u32_e32 v26, vcc, s24, v30
	s_lshl_b64 s[4:5], s[2:3], 15
	s_nop 0
	v_addc_co_u32_e32 v27, vcc, 0, v31, vcc
	global_load_dwordx4 v[26:29], v[26:27], off nt
	v_add_co_u32_e32 v34, vcc, s26, v30
	s_add_u32 s2, s8, s4
	s_nop 0
	v_addc_co_u32_e32 v35, vcc, 0, v31, vcc
	global_load_dwordx4 v[30:33], v[34:35], off offset:-4096 nt
	s_nop 0
	global_load_dwordx4 v[34:37], v[34:35], off nt
	s_addc_u32 s5, s9, s5
	s_lshl_b32 s4, s6, 1
	s_add_u32 s4, s2, s4
	v_mov_b32_e32 v21, v3
	s_addc_u32 s5, s5, 0
	v_lshl_add_u64 v[38:39], s[4:5], 0, v[20:21]
	v_or_b32_e32 v13, s6, v0
	v_add_co_u32_e32 v38, vcc, s25, v38
	v_lshrrev_b32_e32 v13, 7, v13
	s_nop 0
	v_addc_co_u32_e32 v39, vcc, 0, v39, vcc
	v_cmp_le_u32_e32 vcc, v54, v13
	v_add_u32_e32 v19, s6, v79
	v_lshrrev_b32_e32 v19, 7, v19
	v_add_u32_e32 v15, s6, v77
	v_lshrrev_b32_e32 v15, 7, v15
	v_add_u32_e32 v17, s6, v78
	v_lshrrev_b32_e32 v17, 7, v17
	s_waitcnt vmcnt(3)
	v_cndmask_b32_e32 v21, 0, v22, vcc
	v_cmp_lt_u32_e32 vcc, v54, v13
	s_nop 1
	v_cndmask_b32_e32 v22, 0, v23, vcc
	v_cmp_le_u32_e32 vcc, v55, v13
	v_cvt_pk_bf16_f32 v22, v21, v22
	s_nop 0
	v_cndmask_b32_e32 v23, 0, v24, vcc
	v_cmp_le_u32_e32 vcc, v56, v13
	s_nop 1
	v_cndmask_b32_e32 v13, 0, v25, vcc
	v_cmp_le_u32_e32 vcc, v54, v19
	v_cvt_pk_bf16_f32 v23, v23, v13
	global_store_dwordx2 v20, v[22:23], s[4:5]
	s_waitcnt vmcnt(3)
	v_cndmask_b32_e32 v13, 0, v26, vcc
	v_cmp_lt_u32_e32 vcc, v54, v19
	s_nop 1
	v_cndmask_b32_e32 v21, 0, v27, vcc
	v_cmp_le_u32_e32 vcc, v55, v19
	v_cvt_pk_bf16_f32 v22, v13, v21
	s_nop 0
	v_cndmask_b32_e32 v24, 0, v28, vcc
	v_cmp_le_u32_e32 vcc, v56, v19
	s_nop 1
	v_cndmask_b32_e32 v19, 0, v29, vcc
	v_cmp_le_u32_e32 vcc, v54, v15
	v_cvt_pk_bf16_f32 v23, v24, v19
	s_waitcnt vmcnt(2)
	v_cndmask_b32_e32 v25, 0, v30, vcc
	v_cmp_lt_u32_e32 vcc, v54, v15
	s_nop 1
	v_cndmask_b32_e32 v26, 0, v31, vcc
	v_cmp_le_u32_e32 vcc, v55, v15
	v_cvt_pk_bf16_f32 v24, v25, v26
	s_nop 0
	v_cndmask_b32_e32 v27, 0, v32, vcc
	v_cmp_le_u32_e32 vcc, v56, v15
	s_nop 1
	v_cndmask_b32_e32 v15, 0, v33, vcc
	v_cmp_le_u32_e32 vcc, v54, v17
	v_cvt_pk_bf16_f32 v25, v27, v15
	s_waitcnt vmcnt(1)
	v_cndmask_b32_e32 v28, 0, v34, vcc
	v_cmp_lt_u32_e32 vcc, v54, v17
	s_nop 1
	v_cndmask_b32_e32 v29, 0, v35, vcc
	v_cmp_le_u32_e32 vcc, v55, v17
	v_cvt_pk_bf16_f32 v26, v28, v29
	s_nop 0
	v_cndmask_b32_e32 v30, 0, v36, vcc
	v_cmp_le_u32_e32 vcc, v56, v17
	s_nop 1
	v_cndmask_b32_e32 v17, 0, v37, vcc
	v_cvt_pk_bf16_f32 v27, v30, v17
	global_store_dwordx2 v[38:39], v[22:23], off offset:2048
	global_store_dwordx2 v20, v[24:25], s[4:5] offset:2048
	global_store_dwordx2 v[38:39], v[26:27], off
	s_mov_b64 s[4:5], 0
.LBB0_35:
	s_andn2_b64 vcc, exec, s[4:5]
	s_cbranch_vccnz .LBB0_37
	s_add_i32 s2, s40, 0xffffeae0
	v_readlane_b32 s48, v235, 1
	s_lshl_b64 s[4:5], s[2:3], 14
	v_readlane_b32 s60, v235, 13
	v_readlane_b32 s61, v235, 14
	s_add_u32 s4, s60, s4
	s_addc_u32 s5, s61, s5
	v_lshl_add_u64 v[22:23], v[176:177], 2, s[4:5]
	v_lshl_add_u64 v[24:25], v[4:5], 2, s[4:5]
	global_load_dword v17, v[22:23], off nt
	global_load_dword v19, v80, s[4:5] nt
	global_load_dword v21, v81, s[4:5] nt
	global_load_dword v26, v82, s[4:5] nt
	global_load_dword v27, v[24:25], off nt
	global_load_dword v28, v83, s[4:5] nt
	global_load_dword v29, v84, s[4:5] nt
	global_load_dword v34, v85, s[4:5] nt
	v_lshl_add_u64 v[22:23], v[6:7], 2, s[4:5]
	v_lshl_add_u64 v[24:25], v[8:9], 2, s[4:5]
	global_load_dword v35, v[22:23], off nt
	global_load_dword v36, v86, s[4:5] nt
	global_load_dword v37, v87, s[4:5] nt
	global_load_dword v38, v88, s[4:5] nt
	s_nop 0
	global_load_dword v24, v[24:25], off nt
	s_nop 0
	global_load_dword v25, v89, s[4:5] nt
	global_load_dword v39, v90, s[4:5] nt
	global_load_dword v40, v91, s[4:5] nt
	s_lshl_b64 s[4:5], s[2:3], 13
	v_mov_b32_e32 v13, v3
	v_mov_b32_e32 v15, v3
	v_lshl_add_u64 v[22:23], v[10:11], 0, s[4:5]
	v_lshl_add_u64 v[30:31], v[22:23], 0, v[12:13]
	v_lshl_add_u64 v[32:33], v[22:23], 0, v[14:15]
	v_readlane_b32 s49, v235, 2
	v_readlane_b32 s50, v235, 3
	v_readlane_b32 s51, v235, 4
	v_readlane_b32 s52, v235, 5
	v_readlane_b32 s53, v235, 6
	v_readlane_b32 s54, v235, 7
	v_readlane_b32 s55, v235, 8
	v_readlane_b32 s56, v235, 9
	v_readlane_b32 s57, v235, 10
	v_readlane_b32 s58, v235, 11
	v_readlane_b32 s59, v235, 12
	v_readlane_b32 s62, v235, 15
	v_readlane_b32 s63, v235, 16
	s_waitcnt vmcnt(15)
	ds_write_b32 v92, v17
	s_waitcnt vmcnt(14)
	ds_write_b32 v93, v19
	s_waitcnt vmcnt(13)
	ds_write_b32 v94, v21
	s_waitcnt vmcnt(12)
	ds_write_b32 v95, v26
	s_waitcnt vmcnt(11)
	ds_write_b32 v92, v27 offset:4160
	s_waitcnt vmcnt(10)
	ds_write_b32 v96, v28
	s_waitcnt vmcnt(9)
	ds_write_b32 v97, v29
	s_waitcnt vmcnt(8)
	ds_write_b32 v98, v34
	s_waitcnt vmcnt(7)
	ds_write_b32 v92, v35 offset:8320
	s_waitcnt vmcnt(6)
	ds_write_b32 v99, v36
	s_waitcnt vmcnt(5)
	ds_write_b32 v100, v37
	s_waitcnt vmcnt(4)
	ds_write_b32 v101, v38
	s_waitcnt vmcnt(3)
	ds_write_b32 v92, v24 offset:12480
	s_waitcnt vmcnt(2)
	ds_write_b32 v102, v25
	s_waitcnt vmcnt(1)
	ds_write_b32 v103, v39
	s_waitcnt vmcnt(0)
	ds_write_b32 v104, v40
	s_waitcnt lgkmcnt(0)
	s_barrier
	ds_read2_b32 v[22:23], v74 offset1:65
	ds_read2_b32 v[24:25], v74 offset0:130 offset1:195
	ds_read2_b32 v[26:27], v105 offset0:4 offset1:69
	ds_read2_b32 v[28:29], v105 offset0:134 offset1:199
	ds_read2_b32 v[34:35], v76 offset1:65
	ds_read2_b32 v[36:37], v76 offset0:130 offset1:195
	ds_read2_b32 v[38:39], v106 offset0:4 offset1:69
	ds_read2_b32 v[40:41], v106 offset0:134 offset1:199
	s_waitcnt lgkmcnt(7)
	v_cvt_pk_bf16_f32 v22, v22, v23
	s_waitcnt lgkmcnt(6)
	v_cvt_pk_bf16_f32 v23, v24, v25
	s_waitcnt lgkmcnt(5)
	v_cvt_pk_bf16_f32 v24, v26, v27
	s_waitcnt lgkmcnt(4)
	v_cvt_pk_bf16_f32 v25, v28, v29
	s_waitcnt lgkmcnt(3)
	v_cvt_pk_bf16_f32 v26, v34, v35
	s_waitcnt lgkmcnt(2)
	v_cvt_pk_bf16_f32 v27, v36, v37
	s_waitcnt lgkmcnt(1)
	v_cvt_pk_bf16_f32 v28, v38, v39
	s_waitcnt lgkmcnt(0)
	v_cvt_pk_bf16_f32 v29, v40, v41
	global_store_dwordx4 v[30:31], v[22:25], off
	global_store_dwordx4 v[32:33], v[26:29], off
	s_barrier

; DI void tr_tile(const float* src, int ldsrc, u16* dst, int ldd, int k0, int n0, const float* g, int mode, char* lds) {
;   float* t = (float*)lds;
;   const int tid = threadIdx.x;
;   float v[16];
; #pragma unroll
;   for (int i = 0; i < 16; ++i) {
;     const int e = tid + 256 * i, kk = e >> 6, nn = e & 63;
;     const int sc = mapcol(n0 + nn, mode);
;     v[i] = sc >= 0 ? src[(size_t)(k0 + kk) * ldsrc + sc] : 0.f;
;   }
;   if (g) {
; #pragma unroll
;     for (int i = 0; i < 16; ++i) v[i] *= g[k0 + ((tid + 256 * i) >> 6)];
;   }
; #pragma unroll
;   for (int i = 0; i < 16; ++i) { const int e = tid + 256 * i, kk = e >> 6, nn = e & 63; t[kk * 65 + nn] = v[i]; }
;   __syncthreads();
; #pragma unroll
;   for (int i = 0; i < 2; ++i) {
;     const int e = tid + 256 * i, nn = e >> 3, k8 = (e & 7) * 8;
;     u32x4 o;
;     o[0] = pk2(t[(k8 + 0) * 65 + nn], t[(k8 + 1) * 65 + nn]); o[1] = pk2(t[(k8 + 2) * 65 + nn], t[(k8 + 3) * 65 + nn]);
;     o[2] = pk2(t[(k8 + 4) * 65 + nn], t[(k8 + 5) * 65 + nn]); o[3] = pk2(t[(k8 + 6) * 65 + nn], t[(k8 + 7) * 65 + nn]);
;     *(u32x4*)(dst + (size_t)(n0 + nn) * ldd + k0 + k8) = o;
;   }
;   __syncthreads();
; }
; __global__ void __launch_bounds__(256, 2) hybrid_megakernel(Params p) {
;     ...
;     else if (it < 5408) { const int i2 = it - 5376, mtx = i2 >> 2, ktile = i2 & 3;
;       tr_tile(p.w_cmp2 + (size_t)mtx * 256 * 64, 64, (u16*)(ws_ + OFF_W2) + (size_t)mtx * 64 * 256, 256, ktile * 64, 0, nullptr, 0, lds); }
.LBB0_38:
	s_andn2_b64 vcc, exec, s[4:5]
	s_cbranch_vccnz .LBB0_40
	s_add_i32 s2, s40, 0xffffeb00
	s_lshr_b32 s2, s2, 2
	v_readlane_b32 s48, v235, 1
	s_lshl_b64 s[4:5], s[2:3], 16
	v_readlane_b32 s58, v235, 11
	v_readlane_b32 s59, v235, 12
	s_add_u32 s4, s58, s4
	s_addc_u32 s5, s59, s5
	s_lshl_b64 s[6:7], s[2:3], 15
	s_add_u32 s2, s10, s6
	s_addc_u32 s6, s11, s7
	s_and_b32 s7, s16, 0xc0
	v_or_b32_e32 v13, s7, v120
	v_lshl_or_b32 v22, v13, 6, v57
	v_or_b32_e32 v13, s7, v58
	v_lshl_or_b32 v24, v13, 6, v57
	v_or_b32_e32 v13, s7, v59
	v_lshl_or_b32 v26, v13, 6, v57
	v_or_b32_e32 v13, s7, v60
	v_lshl_or_b32 v28, v13, 6, v57
	v_or_b32_e32 v13, s7, v61
	v_lshl_or_b32 v30, v13, 6, v57
	v_or_b32_e32 v13, s7, v62
	v_lshl_or_b32 v32, v13, 6, v57
	v_or_b32_e32 v13, s7, v63
	v_mov_b32_e32 v23, v3
	v_mov_b32_e32 v25, v3
	v_mov_b32_e32 v27, v3
	v_mov_b32_e32 v29, v3
	v_lshl_or_b32 v34, v13, 6, v57
	v_or_b32_e32 v13, s7, v64
	v_lshl_add_u64 v[22:23], v[22:23], 2, s[4:5]
	v_lshl_add_u64 v[24:25], v[24:25], 2, s[4:5]
	v_lshl_add_u64 v[26:27], v[26:27], 2, s[4:5]
	v_lshl_add_u64 v[28:29], v[28:29], 2, s[4:5]
	v_mov_b32_e32 v31, v3
	v_mov_b32_e32 v33, v3
	v_mov_b32_e32 v35, v3
	v_lshl_or_b32 v36, v13, 6, v57
	v_mov_b32_e32 v37, v3
	v_lshl_add_u64 v[30:31], v[30:31], 2, s[4:5]
	v_lshl_add_u64 v[32:33], v[32:33], 2, s[4:5]
	v_lshl_add_u64 v[34:35], v[34:35], 2, s[4:5]
	v_lshl_add_u64 v[36:37], v[36:37], 2, s[4:5]
	global_load_dword v13, v[22:23], off nt
	global_load_dword v15, v[24:25], off nt
	global_load_dword v17, v[26:27], off nt
	global_load_dword v19, v[28:29], off nt
	global_load_dword v21, v[30:31], off nt
	global_load_dword v38, v[32:33], off nt
	global_load_dword v39, v[34:35], off nt
	global_load_dword v40, v[36:37], off nt
	v_or_b32_e32 v22, s7, v65
	v_or_b32_e32 v24, s7, v66
	v_or_b32_e32 v26, s7, v67
	v_or_b32_e32 v28, s7, v68
	v_lshl_or_b32 v22, v22, 6, v57
	v_mov_b32_e32 v23, v3
	v_lshl_or_b32 v24, v24, 6, v57
	v_mov_b32_e32 v25, v3
	v_lshl_or_b32 v26, v26, 6, v57
	v_mov_b32_e32 v27, v3
	v_lshl_or_b32 v28, v28, 6, v57
	v_mov_b32_e32 v29, v3
	v_or_b32_e32 v30, s7, v69
	v_add_u32_e32 v32, s7, v70
	v_add_u32_e32 v34, s7, v71
	v_add_u32_e32 v36, s7, v72
	v_lshl_add_u64 v[22:23], v[22:23], 2, s[4:5]
	v_lshl_add_u64 v[24:25], v[24:25], 2, s[4:5]
	v_lshl_add_u64 v[26:27], v[26:27], 2, s[4:5]
	v_lshl_add_u64 v[28:29], v[28:29], 2, s[4:5]
	v_lshl_or_b32 v30, v30, 6, v57
	v_mov_b32_e32 v31, v3
	v_lshl_or_b32 v32, v32, 6, v57
	v_mov_b32_e32 v33, v3
	v_lshl_or_b32 v34, v34, 6, v57
	v_mov_b32_e32 v35, v3
	v_lshl_or_b32 v36, v36, 6, v57
	v_mov_b32_e32 v37, v3
	v_lshl_add_u64 v[30:31], v[30:31], 2, s[4:5]
	v_lshl_add_u64 v[32:33], v[32:33], 2, s[4:5]
	v_lshl_add_u64 v[34:35], v[34:35], 2, s[4:5]
	v_lshl_add_u64 v[36:37], v[36:37], 2, s[4:5]
	global_load_dword v22, v[22:23], off nt
	s_nop 0
	global_load_dword v23, v[24:25], off nt
	s_nop 0
	global_load_dword v24, v[26:27], off nt
	global_load_dword v25, v[28:29], off nt
	s_nop 0
	global_load_dword v26, v[30:31], off nt
	global_load_dword v27, v[32:33], off nt
	global_load_dword v28, v[34:35], off nt
	global_load_dword v29, v[36:37], off nt
	s_lshl_b32 s4, s7, 1
	s_add_u32 s4, s2, s4
	s_addc_u32 s5, s6, 0
	v_lshl_add_u64 v[30:31], s[4:5], 0, v[2:3]
	v_readlane_b32 s49, v235, 2
	v_readlane_b32 s50, v235, 3
	v_readlane_b32 s51, v235, 4
	v_readlane_b32 s52, v235, 5
	v_readlane_b32 s53, v235, 6
	v_readlane_b32 s54, v235, 7
	v_readlane_b32 s55, v235, 8
	v_readlane_b32 s56, v235, 9
	v_readlane_b32 s57, v235, 10
	v_readlane_b32 s60, v235, 13
	v_readlane_b32 s61, v235, 14
	v_readlane_b32 s62, v235, 15
	v_readlane_b32 s63, v235, 16
	s_waitcnt vmcnt(15)
	ds_write_b32 v92, v13
	s_waitcnt vmcnt(14)
	ds_write_b32 v93, v15
	s_waitcnt vmcnt(13)
	ds_write_b32 v94, v17
	s_waitcnt vmcnt(12)
	ds_write_b32 v95, v19
	s_waitcnt vmcnt(11)
	ds_write_b32 v92, v21 offset:4160
	s_waitcnt vmcnt(10)
	ds_write_b32 v96, v38
	s_waitcnt vmcnt(9)
	ds_write_b32 v97, v39
	s_waitcnt vmcnt(8)
	ds_write_b32 v98, v40
	s_waitcnt vmcnt(7)
	ds_write_b32 v92, v22 offset:8320
	s_waitcnt vmcnt(6)
	ds_write_b32 v99, v23
	s_waitcnt vmcnt(5)
	ds_write_b32 v100, v24
	s_waitcnt vmcnt(4)
	ds_write_b32 v101, v25
	s_waitcnt vmcnt(3)
	ds_write_b32 v92, v26 offset:12480
	s_waitcnt vmcnt(2)
	ds_write_b32 v102, v27
	s_waitcnt vmcnt(1)
	ds_write_b32 v103, v28
	s_waitcnt vmcnt(0)
	ds_write_b32 v104, v29
	s_waitcnt lgkmcnt(0)
	s_barrier
	ds_read2_b32 v[22:23], v74 offset1:65
	ds_read2_b32 v[24:25], v74 offset0:130 offset1:195
	ds_read2_b32 v[26:27], v105 offset0:4 offset1:69
	ds_read2_b32 v[28:29], v105 offset0:134 offset1:199
	v_mov_b32_e32 v17, v3
	s_waitcnt lgkmcnt(3)
	v_cvt_pk_bf16_f32 v22, v22, v23
	s_waitcnt lgkmcnt(2)
	v_cvt_pk_bf16_f32 v23, v24, v25
	s_waitcnt lgkmcnt(1)
	v_cvt_pk_bf16_f32 v24, v26, v27
	s_waitcnt lgkmcnt(0)
	v_cvt_pk_bf16_f32 v25, v28, v29
	ds_read2_b32 v[28:29], v76 offset1:65
	ds_read2_b32 v[32:33], v76 offset0:130 offset1:195
	ds_read2_b32 v[34:35], v106 offset0:4 offset1:69
	ds_read2_b32 v[36:37], v106 offset0:134 offset1:199
	v_lshl_add_u64 v[26:27], v[30:31], 0, v[16:17]
	v_mov_b32_e32 v19, v3
	global_store_dwordx4 v[26:27], v[22:25], off
	v_lshl_add_u64 v[26:27], v[30:31], 0, v[18:19]
	s_waitcnt lgkmcnt(3)
	v_cvt_pk_bf16_f32 v22, v28, v29
	s_waitcnt lgkmcnt(2)
	v_cvt_pk_bf16_f32 v23, v32, v33
	s_waitcnt lgkmcnt(1)
	v_cvt_pk_bf16_f32 v24, v34, v35
	s_waitcnt lgkmcnt(0)
	v_cvt_pk_bf16_f32 v25, v36, v37
	global_store_dwordx4 v[26:27], v[22:25], off
	s_barrier

; DI void tr_tile(const float* src, int ldsrc, u16* dst, int ldd, int k0, int n0, const float* g, int mode, char* lds) {
;   float* t = (float*)lds;
;   const int tid = threadIdx.x;
;   float v[16];
; #pragma unroll
;   for (int i = 0; i < 16; ++i) {
;     const int e = tid + 256 * i, kk = e >> 6, nn = e & 63;
;     const int sc = mapcol(n0 + nn, mode);
;     v[i] = sc >= 0 ? src[(size_t)(k0 + kk) * ldsrc + sc] : 0.f;
;   }
;   if (g) {
; #pragma unroll
;     for (int i = 0; i < 16; ++i) v[i] *= g[k0 + ((tid + 256 * i) >> 6)];
;   }
; #pragma unroll
;   for (int i = 0; i < 16; ++i) { const int e = tid + 256 * i, kk = e >> 6, nn = e & 63; t[kk * 65 + nn] = v[i]; }
;   __syncthreads();
; #pragma unroll
;   for (int i = 0; i < 2; ++i) {
;     const int e = tid + 256 * i, nn = e >> 3, k8 = (e & 7) * 8;
;     u32x4 o;
;     o[0] = pk2(t[(k8 + 0) * 65 + nn], t[(k8 + 1) * 65 + nn]); o[1] = pk2(t[(k8 + 2) * 65 + nn], t[(k8 + 3) * 65 + nn]);
;     o[2] = pk2(t[(k8 + 4) * 65 + nn], t[(k8 + 5) * 65 + nn]); o[3] = pk2(t[(k8 + 6) * 65 + nn], t[(k8 + 7) * 65 + nn]);
;     *(u32x4*)(dst + (size_t)(n0 + nn) * ldd + k0 + k8) = o;
;   }
;   __syncthreads();
; }
; __global__ void __launch_bounds__(256, 2) hybrid_megakernel(Params p) {
;     ...
;     else if (it < 5376) { const int i2 = it - 4352, mtx = i2 >> 7, r = i2 & 127, ntile = r >> 5, ktile = r & 31;
;       tr_tile(p.w_cmp1 + (size_t)mtx * 2048 * 256, 256, (u16*)(ws_ + OFF_W1) + (size_t)mtx * 256 * 2048, 2048, ktile * 64, ntile * 64, nullptr, 0, lds); }
.LBB0_41:
	s_andn2_b64 vcc, exec, s[4:5]
	s_cbranch_vccnz .LBB0_43
	s_add_i32 s2, s40, 0xffffef00
	s_lshr_b32 s2, s2, 7
	v_readlane_b32 s48, v235, 1
	s_lshl_b64 s[4:5], s[2:3], 21
	v_readlane_b32 s56, v235, 9
	v_readlane_b32 s57, v235, 10
	s_add_u32 s4, s56, s4
	s_addc_u32 s5, s57, s5
	s_lshl_b64 s[6:7], s[2:3], 20
	s_add_u32 s2, s12, s6
	s_addc_u32 s6, s13, s7
	s_and_b32 s7, s16, 0x7c0
	s_and_b32 s41, s22, 0xc0
	v_or_b32_e32 v13, s41, v57
	v_or_b32_e32 v15, s7, v120
	v_lshl_or_b32 v22, v15, 8, v13
	v_or_b32_e32 v15, s7, v58
	v_lshl_or_b32 v24, v15, 8, v13
	v_or_b32_e32 v15, s7, v59
	v_lshl_or_b32 v26, v15, 8, v13
	v_or_b32_e32 v15, s7, v60
	v_mov_b32_e32 v23, v3
	v_lshl_or_b32 v28, v15, 8, v13
	v_or_b32_e32 v15, s7, v62
	v_lshl_add_u64 v[22:23], v[22:23], 2, s[4:5]
	v_lshl_or_b32 v32, v15, 8, v13
	v_or_b32_e32 v15, s7, v63
	v_mov_b32_e32 v25, v3
	v_add_co_u32_e32 v30, vcc, s27, v22
	v_lshl_or_b32 v34, v15, 8, v13
	v_or_b32_e32 v15, s7, v64
	v_lshl_add_u64 v[24:25], v[24:25], 2, s[4:5]
	v_mov_b32_e32 v27, v3
	v_mov_b32_e32 v29, v3
	v_addc_co_u32_e32 v31, vcc, 0, v23, vcc
	v_mov_b32_e32 v33, v3
	v_mov_b32_e32 v35, v3
	v_lshl_or_b32 v36, v15, 8, v13
	v_mov_b32_e32 v37, v3
	v_lshl_add_u64 v[26:27], v[26:27], 2, s[4:5]
	v_lshl_add_u64 v[28:29], v[28:29], 2, s[4:5]
	v_lshl_add_u64 v[32:33], v[32:33], 2, s[4:5]
	v_lshl_add_u64 v[34:35], v[34:35], 2, s[4:5]
	v_lshl_add_u64 v[36:37], v[36:37], 2, s[4:5]
	global_load_dword v15, v[22:23], off nt
	global_load_dword v17, v[24:25], off nt
	global_load_dword v19, v[26:27], off nt
	global_load_dword v21, v[28:29], off nt
	global_load_dword v38, v[30:31], off nt
	global_load_dword v39, v[32:33], off nt
	global_load_dword v40, v[34:35], off nt
	global_load_dword v41, v[36:37], off nt
	v_add_co_u32_e32 v24, vcc, s28, v22
	v_or_b32_e32 v26, s7, v66
	s_nop 0
	v_addc_co_u32_e32 v25, vcc, 0, v23, vcc
	v_or_b32_e32 v28, s7, v67
	v_lshl_or_b32 v26, v26, 8, v13
	v_mov_b32_e32 v27, v3
	v_lshl_or_b32 v28, v28, 8, v13
	v_mov_b32_e32 v29, v3
	v_or_b32_e32 v30, s7, v68
	v_add_co_u32_e32 v22, vcc, s29, v22
	v_add_u32_e32 v32, s7, v70
	v_add_u32_e32 v34, s7, v71
	v_add_u32_e32 v36, s7, v72
	v_lshl_add_u64 v[26:27], v[26:27], 2, s[4:5]
	v_lshl_add_u64 v[28:29], v[28:29], 2, s[4:5]
	v_lshl_or_b32 v30, v30, 8, v13
	v_mov_b32_e32 v31, v3
	v_addc_co_u32_e32 v23, vcc, 0, v23, vcc
	v_lshl_or_b32 v32, v32, 8, v13
	v_mov_b32_e32 v33, v3
	v_lshl_or_b32 v34, v34, 8, v13
	v_mov_b32_e32 v35, v3
	v_lshl_or_b32 v36, v36, 8, v13
	v_mov_b32_e32 v37, v3
	v_lshl_add_u64 v[30:31], v[30:31], 2, s[4:5]
	v_lshl_add_u64 v[32:33], v[32:33], 2, s[4:5]
	v_lshl_add_u64 v[34:35], v[34:35], 2, s[4:5]
	v_lshl_add_u64 v[36:37], v[36:37], 2, s[4:5]
	global_load_dword v13, v[24:25], off nt
	s_nop 0
	global_load_dword v24, v[26:27], off nt
	global_load_dword v25, v[28:29], off nt
	s_nop 0
	global_load_dword v26, v[30:31], off nt
	s_nop 0
	global_load_dword v22, v[22:23], off nt
	s_nop 0
	global_load_dword v23, v[32:33], off nt
	global_load_dword v27, v[34:35], off nt
	global_load_dword v28, v[36:37], off nt
	s_lshl_b32 s4, s7, 1
	s_add_u32 s4, s2, s4
	s_addc_u32 s5, s6, 0
	v_lshl_add_u64 v[30:31], s[4:5], 0, v[2:3]
	v_readlane_b32 s49, v235, 2
	v_readlane_b32 s50, v235, 3
	v_readlane_b32 s51, v235, 4
	v_readlane_b32 s52, v235, 5
	v_readlane_b32 s53, v235, 6
	v_readlane_b32 s54, v235, 7
	v_readlane_b32 s55, v235, 8
	v_readlane_b32 s58, v235, 11
	v_readlane_b32 s59, v235, 12
	v_readlane_b32 s60, v235, 13
	v_readlane_b32 s61, v235, 14
	v_readlane_b32 s62, v235, 15
	v_readlane_b32 s63, v235, 16
	s_waitcnt vmcnt(15)
	ds_write_b32 v92, v15
	s_waitcnt vmcnt(14)
	ds_write_b32 v93, v17
	s_waitcnt vmcnt(13)
	ds_write_b32 v94, v19
	s_waitcnt vmcnt(12)
	ds_write_b32 v95, v21
	s_waitcnt vmcnt(11)
	ds_write_b32 v92, v38 offset:4160
	s_waitcnt vmcnt(10)
	ds_write_b32 v96, v39
	s_waitcnt vmcnt(9)
	ds_write_b32 v97, v40
	s_waitcnt vmcnt(8)
	ds_write_b32 v98, v41
	s_waitcnt vmcnt(7)
	ds_write_b32 v92, v13 offset:8320
	s_waitcnt vmcnt(6)
	ds_write_b32 v99, v24
	s_waitcnt vmcnt(5)
	ds_write_b32 v100, v25
	s_waitcnt vmcnt(4)
	ds_write_b32 v101, v26
	s_waitcnt vmcnt(3)
	ds_write_b32 v92, v22 offset:12480
	s_waitcnt vmcnt(2)
	ds_write_b32 v102, v23
	s_waitcnt vmcnt(1)
	ds_write_b32 v103, v27
	s_waitcnt vmcnt(0)
	ds_write_b32 v104, v28
	s_waitcnt lgkmcnt(0)
	s_barrier
	ds_read2_b32 v[22:23], v74 offset1:65
	ds_read2_b32 v[24:25], v74 offset0:130 offset1:195
	ds_read2_b32 v[26:27], v105 offset0:4 offset1:69
	ds_read2_b32 v[28:29], v105 offset0:134 offset1:199
	s_waitcnt lgkmcnt(3)
	v_cvt_pk_bf16_f32 v22, v22, v23
	s_waitcnt lgkmcnt(2)
	v_cvt_pk_bf16_f32 v23, v24, v25
	s_waitcnt lgkmcnt(1)
	v_cvt_pk_bf16_f32 v24, v26, v27
	s_waitcnt lgkmcnt(0)
	v_cvt_pk_bf16_f32 v25, v28, v29
	ds_read2_b32 v[28:29], v76 offset1:65
	ds_read2_b32 v[32:33], v76 offset0:130 offset1:195
	ds_read2_b32 v[34:35], v106 offset0:4 offset1:69
	ds_read2_b32 v[36:37], v106 offset0:134 offset1:199
	v_add_lshl_u32 v26, s41, v73, 12
	v_mov_b32_e32 v27, v3
	v_lshl_add_u64 v[26:27], v[30:31], 0, v[26:27]
	global_store_dwordx4 v[26:27], v[22:25], off
	v_add_lshl_u32 v26, s41, v75, 12
	v_mov_b32_e32 v27, v3
	s_waitcnt lgkmcnt(3)
	v_cvt_pk_bf16_f32 v22, v28, v29
	s_waitcnt lgkmcnt(2)
	v_cvt_pk_bf16_f32 v23, v32, v33
	s_waitcnt lgkmcnt(1)
	v_cvt_pk_bf16_f32 v24, v34, v35
	s_waitcnt lgkmcnt(0)
	v_cvt_pk_bf16_f32 v25, v36, v37
	v_lshl_add_u64 v[26:27], v[30:31], 0, v[26:27]
	global_store_dwordx4 v[26:27], v[22:25], off
	s_barrier

; DI void tr_tile(const float* src, int ldsrc, u16* dst, int ldd, int k0, int n0, const float* g, int mode, char* lds) {
;   float* t = (float*)lds;
;   const int tid = threadIdx.x;
;   float v[16];
; #pragma unroll
;   for (int i = 0; i < 16; ++i) {
;     const int e = tid + 256 * i, kk = e >> 6, nn = e & 63;
;     const int sc = mapcol(n0 + nn, mode);
;     v[i] = sc >= 0 ? src[(size_t)(k0 + kk) * ldsrc + sc] : 0.f;
;   }
;   if (g) {
; #pragma unroll
;     for (int i = 0; i < 16; ++i) v[i] *= g[k0 + ((tid + 256 * i) >> 6)];
;   }
; #pragma unroll
;   for (int i = 0; i < 16; ++i) { const int e = tid + 256 * i, kk = e >> 6, nn = e & 63; t[kk * 65 + nn] = v[i]; }
;   __syncthreads();
; #pragma unroll
;   for (int i = 0; i < 2; ++i) {
;     const int e = tid + 256 * i, nn = e >> 3, k8 = (e & 7) * 8;
;     u32x4 o;
;     o[0] = pk2(t[(k8 + 0) * 65 + nn], t[(k8 + 1) * 65 + nn]); o[1] = pk2(t[(k8 + 2) * 65 + nn], t[(k8 + 3) * 65 + nn]);
;     o[2] = pk2(t[(k8 + 4) * 65 + nn], t[(k8 + 5) * 65 + nn]); o[3] = pk2(t[(k8 + 6) * 65 + nn], t[(k8 + 7) * 65 + nn]);
;     *(u32x4*)(dst + (size_t)(n0 + nn) * ldd + k0 + k8) = o;
;   }
;   __syncthreads();
; }
; __global__ void __launch_bounds__(256, 2) hybrid_megakernel(Params p) {
;     ...
;     else if (it < 4352) { const int i2 = it - 3328, l = i2 >> 8, r = i2 & 255, ntile = r >> 4, ktile = r & 15;
;       tr_tile(p.w_out + (size_t)l * 1024 * 1024, 1024, (u16*)(ws_ + OFF_WOUT) + (size_t)l * 1024 * 1024, 1024, ktile * 64, ntile * 64, nullptr, 0, lds); }
.LBB0_44:
	s_andn2_b64 vcc, exec, s[4:5]
	s_cbranch_vccnz .LBB0_46
	s_add_i32 s2, s40, 0xfffff300
	s_lshr_b32 s2, s2, 8
	s_lshl_b64 s[4:5], s[2:3], 22
	s_add_u32 s4, s84, s4
	s_addc_u32 s5, s85, s5
	s_lshl_b64 s[6:7], s[2:3], 21
	s_add_u32 s2, s14, s6
	s_addc_u32 s6, s15, s7
	s_and_b32 s7, s16, 0x3c0
	s_and_b32 s41, s18, 0x3c0
	v_or_b32_e32 v13, s41, v57
	v_or_b32_e32 v15, s7, v120
	v_lshl_or_b32 v22, v15, 10, v13
	v_or_b32_e32 v15, s7, v58
	v_lshl_or_b32 v24, v15, 10, v13
	v_or_b32_e32 v15, s7, v59
	v_lshl_or_b32 v26, v15, 10, v13
	v_or_b32_e32 v15, s7, v60
	v_mov_b32_e32 v23, v3
	v_lshl_or_b32 v28, v15, 10, v13
	v_or_b32_e32 v15, s7, v62
	v_lshl_add_u64 v[22:23], v[22:23], 2, s[4:5]
	v_lshl_or_b32 v32, v15, 10, v13
	v_or_b32_e32 v15, s7, v63
	v_mov_b32_e32 v25, v3
	v_add_co_u32_e32 v30, vcc, s30, v22
	v_lshl_or_b32 v34, v15, 10, v13
	v_or_b32_e32 v15, s7, v64
	v_lshl_add_u64 v[24:25], v[24:25], 2, s[4:5]
	v_mov_b32_e32 v27, v3
	v_mov_b32_e32 v29, v3
	v_addc_co_u32_e32 v31, vcc, 0, v23, vcc
	v_mov_b32_e32 v33, v3
	v_mov_b32_e32 v35, v3
	v_lshl_or_b32 v36, v15, 10, v13
	v_mov_b32_e32 v37, v3
	v_lshl_add_u64 v[26:27], v[26:27], 2, s[4:5]
	v_lshl_add_u64 v[28:29], v[28:29], 2, s[4:5]
	v_lshl_add_u64 v[32:33], v[32:33], 2, s[4:5]
	v_lshl_add_u64 v[34:35], v[34:35], 2, s[4:5]
	v_lshl_add_u64 v[36:37], v[36:37], 2, s[4:5]
	global_load_dword v15, v[22:23], off nt
	global_load_dword v17, v[24:25], off nt
	global_load_dword v19, v[26:27], off nt
	global_load_dword v21, v[28:29], off nt
	global_load_dword v38, v[30:31], off nt
	global_load_dword v39, v[32:33], off nt
	global_load_dword v40, v[34:35], off nt
	global_load_dword v41, v[36:37], off nt
	v_add_co_u32_e32 v24, vcc, s31, v22
	v_or_b32_e32 v26, s7, v66
	s_nop 0
	v_addc_co_u32_e32 v25, vcc, 0, v23, vcc
	v_or_b32_e32 v28, s7, v67
	v_lshl_or_b32 v26, v26, 10, v13
	v_mov_b32_e32 v27, v3
	v_lshl_or_b32 v28, v28, 10, v13
	v_mov_b32_e32 v29, v3
	v_or_b32_e32 v30, s7, v68
	v_add_co_u32_e32 v22, vcc, s34, v22
	v_add_u32_e32 v32, s7, v70
	v_add_u32_e32 v34, s7, v71
	v_add_u32_e32 v36, s7, v72
	v_lshl_add_u64 v[26:27], v[26:27], 2, s[4:5]
	v_lshl_add_u64 v[28:29], v[28:29], 2, s[4:5]
	v_lshl_or_b32 v30, v30, 10, v13
	v_mov_b32_e32 v31, v3
	v_addc_co_u32_e32 v23, vcc, 0, v23, vcc
	v_lshl_or_b32 v32, v32, 10, v13
	v_mov_b32_e32 v33, v3
	v_lshl_or_b32 v34, v34, 10, v13
	v_mov_b32_e32 v35, v3
	v_lshl_or_b32 v36, v36, 10, v13
	v_mov_b32_e32 v37, v3
	v_lshl_add_u64 v[30:31], v[30:31], 2, s[4:5]
	v_lshl_add_u64 v[32:33], v[32:33], 2, s[4:5]
	v_lshl_add_u64 v[34:35], v[34:35], 2, s[4:5]
	v_lshl_add_u64 v[36:37], v[36:37], 2, s[4:5]
	global_load_dword v13, v[24:25], off nt
	s_nop 0
	global_load_dword v24, v[26:27], off nt
	global_load_dword v25, v[28:29], off nt
	s_nop 0
	global_load_dword v26, v[30:31], off nt
	s_nop 0
	global_load_dword v22, v[22:23], off nt
	s_nop 0
	global_load_dword v23, v[32:33], off nt
	global_load_dword v27, v[34:35], off nt
	global_load_dword v28, v[36:37], off nt
	s_lshl_b32 s4, s7, 1
	s_add_u32 s4, s2, s4
	s_addc_u32 s5, s6, 0
	v_lshl_add_u64 v[30:31], s[4:5], 0, v[2:3]
	s_waitcnt vmcnt(15)
	ds_write_b32 v92, v15
	s_waitcnt vmcnt(14)
	ds_write_b32 v93, v17
	s_waitcnt vmcnt(13)
	ds_write_b32 v94, v19
	s_waitcnt vmcnt(12)
	ds_write_b32 v95, v21
	s_waitcnt vmcnt(11)
	ds_write_b32 v92, v38 offset:4160
	s_waitcnt vmcnt(10)
	ds_write_b32 v96, v39
	s_waitcnt vmcnt(9)
	ds_write_b32 v97, v40
	s_waitcnt vmcnt(8)
	ds_write_b32 v98, v41
	s_waitcnt vmcnt(7)
	ds_write_b32 v92, v13 offset:8320
	s_waitcnt vmcnt(6)
	ds_write_b32 v99, v24
	s_waitcnt vmcnt(5)
	ds_write_b32 v100, v25
	s_waitcnt vmcnt(4)
	ds_write_b32 v101, v26
	s_waitcnt vmcnt(3)
	ds_write_b32 v92, v22 offset:12480
	s_waitcnt vmcnt(2)
	ds_write_b32 v102, v23
	s_waitcnt vmcnt(1)
	ds_write_b32 v103, v27
	s_waitcnt vmcnt(0)
	ds_write_b32 v104, v28
	s_waitcnt lgkmcnt(0)
	s_barrier
	ds_read2_b32 v[22:23], v74 offset1:65
	ds_read2_b32 v[24:25], v74 offset0:130 offset1:195
	ds_read2_b32 v[26:27], v105 offset0:4 offset1:69
	ds_read2_b32 v[28:29], v105 offset0:134 offset1:199
	s_waitcnt lgkmcnt(3)
	v_cvt_pk_bf16_f32 v22, v22, v23
	s_waitcnt lgkmcnt(2)
	v_cvt_pk_bf16_f32 v23, v24, v25
	s_waitcnt lgkmcnt(1)
	v_cvt_pk_bf16_f32 v24, v26, v27
	s_waitcnt lgkmcnt(0)
	v_cvt_pk_bf16_f32 v25, v28, v29
	ds_read2_b32 v[28:29], v76 offset1:65
	ds_read2_b32 v[32:33], v76 offset0:130 offset1:195
	ds_read2_b32 v[34:35], v106 offset0:4 offset1:69
	ds_read2_b32 v[36:37], v106 offset0:134 offset1:199
	v_add_lshl_u32 v26, s41, v73, 11
	v_mov_b32_e32 v27, v3
	v_lshl_add_u64 v[26:27], v[30:31], 0, v[26:27]
	global_store_dwordx4 v[26:27], v[22:25], off
	v_add_lshl_u32 v26, s41, v75, 11
	v_mov_b32_e32 v27, v3
	s_waitcnt lgkmcnt(3)
	v_cvt_pk_bf16_f32 v22, v28, v29
	s_waitcnt lgkmcnt(2)
	v_cvt_pk_bf16_f32 v23, v32, v33
	s_waitcnt lgkmcnt(1)
	v_cvt_pk_bf16_f32 v24, v34, v35
	s_waitcnt lgkmcnt(0)
	v_cvt_pk_bf16_f32 v25, v36, v37
	v_lshl_add_u64 v[26:27], v[30:31], 0, v[26:27]
	global_store_dwordx4 v[26:27], v[22:25], off
	s_barrier

; DI int mapcol(int n, int mode) {
;   if (mode == 0) return n;
;   if (n < 640) return n;
;   if (n < 3200) return n + 12;
;   if (n < 3212) return n - 3200 + 640;
;   return -1;
; }
; DI void tr_tile(const float* src, int ldsrc, u16* dst, int ldd, int k0, int n0, const float* g, int mode, char* lds) {
;   float* t = (float*)lds;
;   const int tid = threadIdx.x;
;   float v[16];
; #pragma unroll
;   for (int i = 0; i < 16; ++i) {
;     const int e = tid + 256 * i, kk = e >> 6, nn = e & 63;
;     const int sc = mapcol(n0 + nn, mode);
;     v[i] = sc >= 0 ? src[(size_t)(k0 + kk) * ldsrc + sc] : 0.f;
;   }
;   if (g) {
; #pragma unroll
;     for (int i = 0; i < 16; ++i) v[i] *= g[k0 + ((tid + 256 * i) >> 6)];
; __global__ void __launch_bounds__(256, 2) hybrid_megakernel(Params p) {
;     ...
;     if (it < 3328) { const int l = it / 832, r = it % 832, ntile = r >> 4, ktile = r & 15;
;       tr_tile(p.w_in + (size_t)l * 1024 * 3212, 3212, (u16*)(ws_ + OFF_WIN) + (size_t)l * NP * 1024, 1024, ktile * 64, ntile * 64, p.g_pre + l * 1024, 1, lds); }
.LBB0_47:
	s_andn2_b64 vcc, exec, s[4:5]
	s_cbranch_vccnz .LBB0_28
	s_mul_hi_i32 s2, s40, 0x4ec4ec4f
	s_lshr_b32 s4, s2, 31
	s_ashr_i32 s42, s2, 8
	s_add_i32 s42, s42, s4
	v_readlane_b32 s48, v235, 1
	s_mul_i32 s4, s42, 0xc8c000
	v_readlane_b32 s52, v235, 5
	s_mul_hi_i32 s2, s42, 0xc8c000
	v_readlane_b32 s53, v235, 6
	s_add_u32 s4, s52, s4
	s_addc_u32 s5, s53, s2
	s_mul_i32 s2, s42, 0xfffff300
	s_add_i32 s6, s18, s2
	s_and_b32 s2, s6, 0xffffffc0
	s_and_b32 s41, s16, 0x3c0
	v_or_b32_e32 v13, s2, v57
	s_cmpk_lt_u32 s6, 0xc80
	v_add_u32_e32 v15, 0xfffff600, v13
	v_cmp_gt_u32_e32 vcc, s36, v13
	v_add_u32_e32 v17, 12, v13
	v_mov_b32_e32 v23, 0
	v_cndmask_b32_e32 v15, -1, v15, vcc
	s_cselect_b64 vcc, -1, 0
	v_cndmask_b32_e32 v15, v15, v17, vcc
	v_cmp_gt_i32_e32 vcc, s35, v13
	v_mov_b32_e32 v22, 0
	v_readlane_b32 s49, v235, 2
	v_cndmask_b32_e32 v19, v15, v13, vcc
	v_cmp_lt_i32_e32 vcc, -1, v19
	v_or_b32_e32 v13, s41, v120
	v_readlane_b32 s50, v235, 3
	v_readlane_b32 s51, v235, 4
	v_readlane_b32 s54, v235, 7
	v_readlane_b32 s55, v235, 8
	v_readlane_b32 s56, v235, 9
	v_readlane_b32 s57, v235, 10
	v_readlane_b32 s58, v235, 11
	v_readlane_b32 s59, v235, 12
	v_readlane_b32 s60, v235, 13
	v_readlane_b32 s61, v235, 14
	v_readlane_b32 s62, v235, 15
	v_readlane_b32 s63, v235, 16
	s_and_saveexec_b64 s[6:7], vcc
	s_cbranch_execz .LBB0_50
	v_mad_u32_u24 v24, v13, s36, v19
	v_mov_b32_e32 v25, v3
	v_lshl_add_u64 v[24:25], v[24:25], 2, s[4:5]
	global_load_dword v22, v[24:25], off nt
.LBB0_50:
	s_or_b64 exec, exec, s[6:7]
	v_or_b32_e32 v15, s41, v58
	s_and_saveexec_b64 s[6:7], vcc
	s_cbranch_execz .LBB0_52
	v_mad_u32_u24 v24, v15, s36, v19
	v_mov_b32_e32 v25, v3
	v_lshl_add_u64 v[24:25], v[24:25], 2, s[4:5]
	global_load_dword v23, v[24:25], off nt
.LBB0_52:
	s_or_b64 exec, exec, s[6:7]
	v_mov_b32_e32 v25, 0
	v_or_b32_e32 v17, s41, v59
	v_mov_b32_e32 v24, 0
	s_and_saveexec_b64 s[6:7], vcc
	s_cbranch_execz .LBB0_54
	v_mad_u32_u24 v26, v17, s36, v19
	v_mov_b32_e32 v27, v3
	v_lshl_add_u64 v[26:27], v[26:27], 2, s[4:5]
	global_load_dword v24, v[26:27], off nt
.LBB0_54:
	s_or_b64 exec, exec, s[6:7]
	v_or_b32_e32 v21, s41, v60
	s_and_saveexec_b64 s[6:7], vcc
	s_cbranch_execz .LBB0_56
	v_mad_u32_u24 v26, v21, s36, v19
	v_mov_b32_e32 v27, v3
	v_lshl_add_u64 v[26:27], v[26:27], 2, s[4:5]
	global_load_dword v25, v[26:27], off nt
.LBB0_56:
	s_or_b64 exec, exec, s[6:7]
	v_mov_b32_e32 v27, 0
	v_mul_u32_u24_e32 v36, 0xc8c, v13
	v_mov_b32_e32 v26, 0
	s_and_saveexec_b64 s[6:7], vcc
	s_cbranch_execz .LBB0_58
	v_add3_u32 v28, v36, v19, s37
	v_mov_b32_e32 v29, v3
	v_lshl_add_u64 v[28:29], v[28:29], 2, s[4:5]
	global_load_dword v26, v[28:29], off nt
.LBB0_58:
	s_or_b64 exec, exec, s[6:7]
	v_or_b32_e32 v38, s41, v62
	s_and_saveexec_b64 s[6:7], vcc
	s_cbranch_execz .LBB0_60
	v_mad_u32_u24 v28, v38, s36, v19
	v_mov_b32_e32 v29, v3
	v_lshl_add_u64 v[28:29], v[28:29], 2, s[4:5]
	global_load_dword v27, v[28:29], off nt
.LBB0_60:
	s_or_b64 exec, exec, s[6:7]
	v_mov_b32_e32 v29, 0
	v_or_b32_e32 v39, s41, v63
	v_mov_b32_e32 v28, 0
	s_and_saveexec_b64 s[6:7], vcc
	s_cbranch_execz .LBB0_62
	v_mad_u32_u24 v30, v39, s36, v19
	v_mov_b32_e32 v31, v3
	v_lshl_add_u64 v[30:31], v[30:31], 2, s[4:5]
	global_load_dword v28, v[30:31], off nt
.LBB0_62:
	s_or_b64 exec, exec, s[6:7]
	v_or_b32_e32 v40, s41, v64
	s_and_saveexec_b64 s[6:7], vcc
	s_cbranch_execz .LBB0_64
	v_mad_u32_u24 v30, v40, s36, v19
	v_mov_b32_e32 v31, v3
	v_lshl_add_u64 v[30:31], v[30:31], 2, s[4:5]
	global_load_dword v29, v[30:31], off nt
.LBB0_64:
	s_or_b64 exec, exec, s[6:7]
	v_mov_b32_e32 v31, 0
	v_mov_b32_e32 v30, 0
	s_and_saveexec_b64 s[6:7], vcc
	s_cbranch_execz .LBB0_66
	v_add3_u32 v32, v36, v19, s38
	v_mov_b32_e32 v33, v3
	v_lshl_add_u64 v[32:33], v[32:33], 2, s[4:5]
	global_load_dword v30, v[32:33], off nt
.LBB0_66:
	s_or_b64 exec, exec, s[6:7]
	v_or_b32_e32 v41, s41, v66
	s_and_saveexec_b64 s[6:7], vcc
	s_cbranch_execz .LBB0_68
	v_mad_u32_u24 v32, v41, s36, v19
	v_mov_b32_e32 v33, v3
	v_lshl_add_u64 v[32:33], v[32:33], 2, s[4:5]
	global_load_dword v31, v[32:33], off nt
.LBB0_68:
	s_or_b64 exec, exec, s[6:7]
	v_mov_b32_e32 v33, 0
	v_or_b32_e32 v42, s41, v67
	v_mov_b32_e32 v32, 0
	s_and_saveexec_b64 s[6:7], vcc
	s_cbranch_execz .LBB0_70
	v_mad_u32_u24 v34, v42, s36, v19
	v_mov_b32_e32 v35, v3
	v_lshl_add_u64 v[34:35], v[34:35], 2, s[4:5]
	global_load_dword v32, v[34:35], off nt
.LBB0_70:
	s_or_b64 exec, exec, s[6:7]
	v_or_b32_e32 v43, s41, v68
	s_and_saveexec_b64 s[6:7], vcc
	s_cbranch_execz .LBB0_72
	v_mad_u32_u24 v34, v43, s36, v19
	v_mov_b32_e32 v35, v3
	v_lshl_add_u64 v[34:35], v[34:35], 2, s[4:5]
	global_load_dword v33, v[34:35], off nt
.LBB0_72:
	s_or_b64 exec, exec, s[6:7]
	v_mov_b32_e32 v35, 0
	v_mov_b32_e32 v34, 0
	s_and_saveexec_b64 s[6:7], vcc
	s_cbranch_execz .LBB0_74
	v_add3_u32 v36, v36, v19, s39
	v_mov_b32_e32 v37, v3
	v_lshl_add_u64 v[36:37], v[36:37], 2, s[4:5]
	global_load_dword v34, v[36:37], off nt
.LBB0_74:
	s_or_b64 exec, exec, s[6:7]
	s_and_saveexec_b64 s[6:7], vcc
	s_cbranch_execz .LBB0_76
	v_add_u32_e32 v35, s41, v70
	v_mad_u32_u24 v36, v35, s36, v19
	v_mov_b32_e32 v37, v3
	v_lshl_add_u64 v[36:37], v[36:37], 2, s[4:5]
	global_load_dword v35, v[36:37], off nt
.LBB0_76:
	s_or_b64 exec, exec, s[6:7]
	v_mov_b32_e32 v37, 0
	v_mov_b32_e32 v36, 0
	s_and_saveexec_b64 s[6:7], vcc
	s_cbranch_execz .LBB0_80
	v_add_u32_e32 v36, s41, v71
	v_mad_u32_u24 v44, v36, s36, v19
	v_mov_b32_e32 v45, v3
	v_lshl_add_u64 v[44:45], v[44:45], 2, s[4:5]
	global_load_dword v36, v[44:45], off nt
	s_or_b64 exec, exec, s[6:7]
	s_and_saveexec_b64 s[6:7], vcc
	s_cbranch_execnz .LBB0_81

; DI void tr_tile(const float* src, int ldsrc, u16* dst, int ldd, int k0, int n0, const float* g, int mode, char* lds) {
;     ...
;   if (g) {
; #pragma unroll
;     for (int i = 0; i < 16; ++i) v[i] *= g[k0 + ((tid + 256 * i) >> 6)];
;   }
.LBB0_79:
	s_lshl_b32 s4, s42, 10
	s_ashr_i32 s5, s4, 31
	v_readlane_b32 s48, v235, 1
	s_lshl_b64 s[4:5], s[4:5], 2
	v_readlane_b32 s50, v235, 3
	v_readlane_b32 s51, v235, 4
	s_add_u32 s4, s50, s4
	s_addc_u32 s5, s51, s5
	v_lshlrev_b32_e32 v13, 2, v13
	v_lshlrev_b32_e32 v15, 2, v15
	v_lshlrev_b32_e32 v17, 2, v17
	v_lshlrev_b32_e32 v44, 2, v38
	v_lshlrev_b32_e32 v45, 2, v39
	v_lshlrev_b32_e32 v47, 2, v40
	v_lshlrev_b32_e32 v19, 2, v21
	v_add_lshl_u32 v21, s41, v120, 2
	v_lshlrev_b32_e32 v48, 2, v41
	v_lshlrev_b32_e32 v49, 2, v42
	v_lshlrev_b32_e32 v50, 2, v43
	global_load_dword v38, v13, s[4:5] nt
	global_load_dword v39, v15, s[4:5] nt
	global_load_dword v40, v17, s[4:5] nt
	global_load_dword v41, v19, s[4:5] nt
	global_load_dword v42, v21, s[4:5] offset:64 nt
	global_load_dword v43, v44, s[4:5] nt
	s_nop 0
	global_load_dword v44, v21, s[4:5] offset:128 nt
	global_load_dword v108, v21, s[4:5] offset:192 nt
	v_add_lshl_u32 v13, s41, v70, 2
	v_add_lshl_u32 v15, s41, v71, 2
	v_add_lshl_u32 v17, s41, v72, 2
	global_load_dword v46, v45, s[4:5] nt
	s_nop 0
	global_load_dword v47, v47, s[4:5] nt
	s_nop 0
	global_load_dword v45, v48, s[4:5] nt
	global_load_dword v110, v49, s[4:5] nt
	global_load_dword v111, v50, s[4:5] nt
	global_load_dword v109, v13, s[4:5] nt
	global_load_dword v112, v15, s[4:5] nt
	global_load_dword v113, v17, s[4:5] nt
	v_readlane_b32 s49, v235, 2
	v_readlane_b32 s52, v235, 5
	v_readlane_b32 s53, v235, 6
	v_readlane_b32 s54, v235, 7
	v_readlane_b32 s55, v235, 8
	v_readlane_b32 s56, v235, 9
	v_readlane_b32 s57, v235, 10
	v_readlane_b32 s58, v235, 11
	v_readlane_b32 s59, v235, 12
	v_readlane_b32 s60, v235, 13
	v_readlane_b32 s61, v235, 14
	v_readlane_b32 s62, v235, 15
	v_readlane_b32 s63, v235, 16
	s_waitcnt vmcnt(14)
	v_pk_mul_f32 v[52:53], v[22:23], v[38:39]
	s_waitcnt vmcnt(12)
	v_pk_mul_f32 v[50:51], v[24:25], v[40:41]
	s_waitcnt vmcnt(10)
	v_pk_mul_f32 v[48:49], v[26:27], v[42:43]
	s_waitcnt vmcnt(6)
	v_pk_mul_f32 v[46:47], v[28:29], v[46:47]
	s_waitcnt vmcnt(5)
	v_pk_mul_f32 v[44:45], v[30:31], v[44:45]
	s_waitcnt vmcnt(3)
	v_pk_mul_f32 v[42:43], v[32:33], v[110:111]
	s_waitcnt vmcnt(2)
	v_pk_mul_f32 v[40:41], v[34:35], v[108:109]
	s_waitcnt vmcnt(0)
	v_pk_mul_f32 v[38:39], v[36:37], v[112:113]
	s_cbranch_execnz .LBB0_27
	s_branch .LBB0_26

; DI void tr_tile(const float* src, int ldsrc, u16* dst, int ldd, int k0, int n0, const float* g, int mode, char* lds) {
;     ...
;   for (int i = 0; i < 16; ++i) {
;     const int e = tid + 256 * i, kk = e >> 6, nn = e & 63;
;     const int sc = mapcol(n0 + nn, mode);
;     v[i] = sc >= 0 ? src[(size_t)(k0 + kk) * ldsrc + sc] : 0.f;
;   }
.LBB0_81:
	v_add_u32_e32 v37, s41, v72
	v_mad_u32_u24 v44, v37, s36, v19
	v_mov_b32_e32 v45, v3
	v_lshl_add_u64 v[44:45], v[44:45], 2, s[4:5]
	global_load_dword v37, v[44:45], off nt
	s_or_b64 exec, exec, s[6:7]
	s_and_b64 vcc, exec, s[0:1]
	s_cbranch_vccnz .LBB0_79

; DI int tidx() { int t = threadIdx.x; asm volatile("" : "+v"(t)); return t; }
; template <int NR>
; DI void rows_convert(const float* x0, u16* xb0, float* rn0) {
;   const int lane = tidx() & 63;
;   f32x4 v[NR][4];
; #pragma unroll
;   for (int r = 0; r < NR; ++r)
; #pragma unroll
;     for (int i = 0; i < 4; ++i) v[r][i] = *(const f32x4*)(x0 + (size_t)r * 1024 + i * 256 + lane * 4);
; #pragma unroll
;   for (int r = 0; r < NR; ++r) {
;     float ss = 0.f;
; #pragma unroll
;     for (int i = 0; i < 4; ++i) {
;       ss += v[r][i][0] * v[r][i][0] + v[r][i][1] * v[r][i][1] + v[r][i][2] * v[r][i][2] + v[r][i][3] * v[r][i][3];
;       u32x2 o; o[0] = pk2(v[r][i][0], v[r][i][1]); o[1] = pk2(v[r][i][2], v[r][i][3]);
;       *(u32x2*)(xb0 + (size_t)r * 1024 + i * 256 + lane * 4) = o;
;     }
;     ss = wave_sum(ss);
;     if (lane == 0) rn0[r] = rsqrtf(ss * (1.f / 1024.f) + 1e-6f);
;   }
; }
; __global__ void __launch_bounds__(256, 2) hybrid_megakernel(Params p) {
;     ...
;   for (int it = bid; it < T_ / 32; it += nb) {
;     const int row = it * 32 + wid * 8;
;     rows_convert<8>(p.x + (size_t)row * 1024, (u16*)(ws_ + OFF_XB) + (size_t)row * 1024, (float*)(ws_ + OFF_RN) + row);
;   }
.LBB0_86:
	v_ashrrev_i32_e32 v113, 31, v112
	v_readlane_b32 s48, v235, 1
	v_mov_b32_e32 v2, v176
	v_lshlrev_b64 v[0:1], 12, v[112:113]
	v_readlane_b32 s49, v235, 2
	v_lshlrev_b64 v[118:119], 11, v[112:113]
	v_and_b32_e32 v135, 63, v2
	v_lshl_add_u64 v[0:1], s[48:49], 0, v[0:1]
	v_lshlrev_b32_e32 v114, 4, v135
	v_lshl_add_u64 v[0:1], v[0:1], 0, v[114:115]
	global_load_dwordx4 v[136:139], v[0:1], off nt
	global_load_dwordx4 v[140:143], v[0:1], off offset:1024 nt
	global_load_dwordx4 v[144:147], v[0:1], off offset:2048 nt
	global_load_dwordx4 v[148:151], v[0:1], off offset:3072 nt
	v_add_co_u32_e32 v2, vcc, s9, v0
	v_lshl_add_u64 v[118:119], s[2:3], 0, v[118:119]
	s_nop 0
	v_addc_co_u32_e32 v3, vcc, 0, v1, vcc
	v_add_co_u32_e32 v108, vcc, s10, v0
	v_lshl_add_u64 v[116:117], v[112:113], 2, s[4:5]
	s_nop 0
	v_addc_co_u32_e32 v109, vcc, 0, v1, vcc
	v_add_co_u32_e32 v4, vcc, s11, v0
	global_load_dwordx4 v[100:103], v[2:3], off offset:1024 nt
	global_load_dwordx4 v[96:99], v[2:3], off offset:2048 nt
	global_load_dwordx4 v[92:95], v[108:109], off nt
	global_load_dwordx4 v[88:91], v[108:109], off offset:1024 nt
	global_load_dwordx4 v[84:87], v[108:109], off offset:2048 nt
	global_load_dwordx4 v[80:83], v[108:109], off offset:3072 nt
	s_waitcnt lgkmcnt(0)
	v_addc_co_u32_e32 v5, vcc, 0, v1, vcc
	v_add_co_u32_e32 v6, vcc, s12, v0
	v_cmp_eq_u32_e64 s[0:1], 0, v135
	s_nop 0
	v_addc_co_u32_e32 v7, vcc, 0, v1, vcc
	global_load_dwordx4 v[104:107], v[2:3], off offset:3072 nt
	global_load_dwordx4 v[72:75], v[4:5], off offset:1024 nt
	global_load_dwordx4 v[68:71], v[4:5], off offset:2048 nt
	global_load_dwordx4 v[64:67], v[4:5], off offset:3072 nt
	global_load_dwordx4 v[76:79], v[6:7], off offset:-4096 nt
	global_load_dwordx4 v[60:63], v[6:7], off nt
	global_load_dwordx4 v[52:55], v[6:7], off offset:1024 nt
	global_load_dwordx4 v[48:51], v[6:7], off offset:2048 nt
	v_add_co_u32_e32 v2, vcc, s13, v0
	v_readlane_b32 s50, v235, 3
	s_nop 0
	v_addc_co_u32_e32 v3, vcc, 0, v1, vcc
	v_add_co_u32_e32 v4, vcc, s14, v0
	v_readlane_b32 s51, v235, 4
	s_nop 0
	v_addc_co_u32_e32 v5, vcc, 0, v1, vcc
	global_load_dwordx4 v[56:59], v[6:7], off offset:3072 nt
	global_load_dwordx4 v[44:47], v[4:5], off offset:-4096 nt
	global_load_dwordx4 v[36:39], v[2:3], off offset:1024 nt
	global_load_dwordx4 v[32:35], v[2:3], off offset:2048 nt
	global_load_dwordx4 v[28:31], v[4:5], off nt
	global_load_dwordx4 v[24:27], v[4:5], off offset:1024 nt
	global_load_dwordx4 v[20:23], v[4:5], off offset:2048 nt
	global_load_dwordx4 v[16:19], v[4:5], off offset:3072 nt
	v_add_co_u32_e32 v0, vcc, s15, v0
	v_readlane_b32 s52, v235, 5
	s_nop 0
	v_addc_co_u32_e32 v1, vcc, 0, v1, vcc
	global_load_dwordx4 v[40:43], v[2:3], off offset:3072 nt
	global_load_dwordx4 v[12:15], v[0:1], off nt
	global_load_dwordx4 v[8:11], v[0:1], off offset:1024 nt
	global_load_dwordx4 v[4:7], v[0:1], off offset:2048 nt
	s_nop 0
	global_load_dwordx4 v[108:111], v[108:109], off offset:-4096 nt
	s_nop 0
	global_load_dwordx4 v[0:3], v[0:1], off offset:3072 nt
	v_cmp_lt_i32_e32 vcc, v124, v123
	v_readlane_b32 s53, v235, 6
	v_readlane_b32 s54, v235, 7
	v_cndmask_b32_e32 v114, v122, v124, vcc
	v_cmp_lt_i32_e32 vcc, v125, v123
	v_lshlrev_b32_e32 v131, 2, v114
	v_lshlrev_b32_e32 v114, 3, v135
	v_cndmask_b32_e32 v132, v122, v125, vcc
	v_lshlrev_b32_e32 v113, 2, v132
	v_lshl_add_u64 v[118:119], v[118:119], 0, v[114:115]
	v_cmp_lt_i32_e32 vcc, v126, v123
	v_readlane_b32 s55, v235, 8
	v_readlane_b32 s56, v235, 9
	v_readlane_b32 s57, v235, 10
	v_readlane_b32 s58, v235, 11
	v_readlane_b32 s59, v235, 12
	v_readlane_b32 s60, v235, 13
	v_readlane_b32 s61, v235, 14
	v_readlane_b32 s62, v235, 15
	v_readlane_b32 s63, v235, 16
	s_waitcnt vmcnt(31)
	v_mul_f32_e32 v114, v137, v137
	s_waitcnt vmcnt(30)
	v_mul_f32_e32 v132, v141, v141
	v_fmac_f32_e32 v114, v136, v136
	v_fmac_f32_e32 v132, v140, v140
	v_fmac_f32_e32 v114, v138, v138
	v_fmac_f32_e32 v132, v142, v142
	s_waitcnt vmcnt(29)
	v_mul_f32_e32 v133, v145, v145
	v_fmac_f32_e32 v114, v139, v139
	v_fmac_f32_e32 v132, v143, v143
	v_fmac_f32_e32 v133, v144, v144
	v_add_f32_e32 v114, v114, v132
	s_waitcnt vmcnt(28)
	v_mul_f32_e32 v132, v149, v149
	v_fmac_f32_e32 v133, v146, v146
	v_fmac_f32_e32 v132, v148, v148
	v_fmac_f32_e32 v133, v147, v147
	v_fmac_f32_e32 v132, v150, v150
	v_add_f32_e32 v114, v114, v133
	v_fmac_f32_e32 v132, v151, v151
	v_add_f32_e32 v114, v114, v132
	ds_bpermute_b32 v133, v131, v114
	v_cndmask_b32_e32 v132, v122, v126, vcc
	v_lshlrev_b32_e32 v132, 2, v132
	v_cmp_lt_i32_e32 vcc, v127, v123
	v_cvt_pk_bf16_f32 v136, v136, v137
	s_waitcnt lgkmcnt(0)
	v_add_f32_e32 v114, v114, v133
	ds_bpermute_b32 v152, v113, v114
	v_cndmask_b32_e32 v134, v122, v127, vcc
	v_lshlrev_b32_e32 v134, 2, v134
	v_cmp_lt_i32_e32 vcc, v128, v123
	v_cvt_pk_bf16_f32 v137, v138, v139
	s_waitcnt lgkmcnt(0)
	v_add_f32_e32 v152, v114, v152
	ds_bpermute_b32 v153, v132, v152
	v_cndmask_b32_e32 v133, v122, v128, vcc
	v_lshlrev_b32_e32 v133, 2, v133
	global_store_dwordx2 v[118:119], v[136:137], off
	v_cvt_pk_bf16_f32 v136, v140, v141
	s_waitcnt lgkmcnt(0)
	v_add_f32_e32 v135, v152, v153
	ds_bpermute_b32 v152, v134, v135
	v_cmp_lt_i32_e32 vcc, v129, v123
	v_cvt_pk_bf16_f32 v137, v142, v143
	global_store_dwordx2 v[118:119], v[136:137], off offset:512
	v_cndmask_b32_e32 v114, v122, v129, vcc
	s_waitcnt lgkmcnt(0)
	v_add_f32_e32 v135, v135, v152
	ds_bpermute_b32 v140, v133, v135
	v_lshlrev_b32_e32 v114, 2, v114
	v_cvt_pk_bf16_f32 v138, v144, v145
	v_cvt_pk_bf16_f32 v139, v146, v147
	global_store_dwordx2 v[118:119], v[138:139], off offset:1024
	s_waitcnt lgkmcnt(0)
	v_add_f32_e32 v135, v135, v140
	ds_bpermute_b32 v136, v114, v135
	v_cvt_pk_bf16_f32 v138, v148, v149
	v_cvt_pk_bf16_f32 v139, v150, v151
	global_store_dwordx2 v[118:119], v[138:139], off offset:1536
	s_and_saveexec_b64 s[6:7], s[0:1]
	s_cbranch_execz .LBB0_88
	s_waitcnt lgkmcnt(0)
	v_add_f32_e32 v135, v135, v136
	v_fmamk_f32 v135, v135, 0x3a800000, v130
	v_mul_f32_e32 v136, 0x4b800000, v135
	v_cmp_gt_f32_e32 vcc, s16, v135
	s_nop 1
	v_cndmask_b32_e32 v135, v135, v136, vcc
	v_rsq_f32_e32 v135, v135
	s_nop 0
	v_mul_f32_e32 v136, 0x45800000, v135
	v_cndmask_b32_e32 v135, v135, v136, vcc
	global_store_dword v[116:117], v135, off
